# attention: waves skip K/V tiles entirely beyond their last query (still issue DMA + take the barrier)
# speedup vs baseline: 1.0066x; 1.0066x over previous
.LBB0_689:
	s_add_i32 s4, s21, -1
	s_min_u32 s4, s4, s43
	s_mul_hi_u32 s5, s4, 0x55555556
	s_mul_i32 s5, s5, 3
	s_sub_i32 s5, s4, s5
	s_mul_i32 s4, s4, 0x28000
	s_lshl_b32 s5, s5, 14
	s_lshl_b32 s80, s4, 1
	s_add_i32 s50, s21, -2
	s_add_i32 s53, s5, 0
	v_lshl_add_u64 v[64:65], v[146:147], 0, s[80:81]
	s_mov_b64 s[4:5], 0xf40
	s_min_u32 s51, s50, s43
	v_lshl_add_u64 v[64:65], v[64:65], 0, s[4:5]
	s_mul_hi_u32 s4, s51, 0x55555556
	s_mul_i32 s4, s4, 3
	s_sub_i32 s4, s51, s4
	s_lshl_b32 s4, s4, 14
	s_add_i32 m0, s53, s89
	s_add_i32 s52, s4, 0
	s_mul_i32 s4, s51, 0x50000
	s_mov_b32 s5, s81
	global_load_lds_dwordx4 v[64:65], off
	v_lshl_add_u64 v[64:65], v[148:149], 0, s[4:5]
	s_add_i32 s4, s52, s95
	s_add_i32 m0, s4, 0x2000
	s_sub_i32 s4, s49, 64
	global_load_lds_dwordx4 v[64:65], off
	s_cmp_le_u32 s4, s39
	s_sub_i32 s5, s4, 94
	s_cmp_gt_i32 s5, s39
	s_cbranch_scc1 .Ltsk689_d1
	s_cmp_le_u32 s4, s39
	s_cbranch_scc1 .LBB0_691
	v_cmp_lt_i32_e64 s[4:5], -1, v156
	v_cmp_lt_i32_e64 s[6:7], 31, v156
	v_cmp_lt_i32_e32 vcc, 0, v156
	v_cndmask_b32_e64 v48, v249, v48, s[4:5]
	v_cmp_lt_i32_e64 s[4:5], 32, v156
	v_cndmask_b32_e64 v32, v249, v32, s[6:7]
	v_cmp_lt_i32_e64 s[6:7], 1, v156
	v_cndmask_b32_e32 v49, v249, v49, vcc
	v_cmp_lt_i32_e32 vcc, 33, v156
	v_cndmask_b32_e64 v33, v249, v33, s[4:5]
	v_cmp_lt_i32_e64 s[4:5], 2, v156
	v_cndmask_b32_e64 v50, v249, v50, s[6:7]
	v_cmp_lt_i32_e64 s[6:7], 34, v156
	v_cndmask_b32_e32 v34, v249, v34, vcc
	v_cmp_lt_i32_e32 vcc, 7, v156
	v_cndmask_b32_e64 v51, v249, v51, s[4:5]
	v_cmp_lt_i32_e64 s[4:5], 39, v156
	v_cndmask_b32_e64 v35, v249, v35, s[6:7]
	v_cmp_lt_i32_e64 s[6:7], 8, v156
	v_cndmask_b32_e32 v52, v249, v52, vcc
	v_cmp_lt_i32_e32 vcc, 40, v156
	v_cndmask_b32_e64 v36, v249, v36, s[4:5]
	v_cmp_lt_i32_e64 s[4:5], 9, v156
	v_cndmask_b32_e64 v53, v249, v53, s[6:7]
	v_cmp_lt_i32_e64 s[6:7], 41, v156
	v_cndmask_b32_e32 v37, v249, v37, vcc
	v_cmp_lt_i32_e32 vcc, 10, v156
	v_cndmask_b32_e64 v54, v249, v54, s[4:5]
	v_cmp_lt_i32_e64 s[4:5], 42, v156
	v_cndmask_b32_e64 v38, v249, v38, s[6:7]
	v_cmp_lt_i32_e64 s[6:7], 15, v156
	v_cndmask_b32_e32 v55, v249, v55, vcc
	v_cmp_lt_i32_e32 vcc, 47, v156
	v_cndmask_b32_e64 v39, v249, v39, s[4:5]
	v_cmp_lt_i32_e64 s[4:5], 16, v156
	v_cndmask_b32_e64 v56, v249, v56, s[6:7]
	v_cmp_lt_i32_e64 s[6:7], 48, v156
	v_cndmask_b32_e32 v40, v249, v40, vcc
	v_cmp_lt_i32_e32 vcc, 17, v156
	v_cndmask_b32_e64 v57, v249, v57, s[4:5]
	v_cmp_lt_i32_e64 s[4:5], 49, v156
	v_cndmask_b32_e64 v41, v249, v41, s[6:7]
	v_cmp_lt_i32_e64 s[6:7], 18, v156
	v_cndmask_b32_e32 v58, v249, v58, vcc
	v_cmp_lt_i32_e32 vcc, 50, v156
	v_cndmask_b32_e64 v42, v249, v42, s[4:5]
	v_cmp_lt_i32_e64 s[4:5], 23, v156
	v_cndmask_b32_e64 v59, v249, v59, s[6:7]
	v_cmp_lt_i32_e64 s[6:7], 55, v156
	v_cndmask_b32_e32 v43, v249, v43, vcc
	v_cmp_lt_i32_e32 vcc, 24, v156
	v_cndmask_b32_e64 v60, v249, v60, s[4:5]
	v_cmp_lt_i32_e64 s[4:5], 56, v156
	v_cndmask_b32_e64 v44, v249, v44, s[6:7]
	v_cmp_lt_i32_e64 s[6:7], 25, v156
	v_cndmask_b32_e32 v61, v249, v61, vcc
	v_cmp_lt_i32_e32 vcc, 57, v156
	v_cndmask_b32_e64 v45, v249, v45, s[4:5]
	v_cmp_lt_i32_e64 s[4:5], 26, v156
	v_cndmask_b32_e64 v62, v249, v62, s[6:7]
	v_cmp_lt_i32_e64 s[6:7], 58, v156
	v_cndmask_b32_e32 v46, v249, v46, vcc
	s_nop 0
	v_cndmask_b32_e64 v63, v249, v63, s[4:5]
	s_nop 0
	v_cndmask_b32_e64 v47, v249, v47, s[6:7]

.Ltsk689_s2:
	s_min_u32 s4, s21, s43
	s_mul_hi_u32 s5, s4, 0x55555556
	s_mul_i32 s5, s5, 3
	s_sub_i32 s5, s4, s5
	s_lshl_b32 s6, s5, 14
	s_mul_i32 s4, s4, 0x50000
	s_mov_b32 s5, s81
	v_lshl_add_u64 v[32:33], v[146:147], 0, s[4:5]
	s_mov_b64 s[4:5], 0xf40
	v_lshl_add_u64 v[32:33], v[32:33], 0, s[4:5]
	s_add_i32 m0, s61, s6
	s_add_i32 s4, s53, s95
	global_load_lds_dwordx4 v[32:33], off
	v_lshl_add_u64 v[32:33], v[148:149], 0, s[80:81]
	s_add_i32 m0, s4, 0x2000
	s_cmp_le_u32 s49, s39
	global_load_lds_dwordx4 v[32:33], off
	s_sub_i32 s5, s49, 94
	s_cmp_gt_i32 s5, s39
	s_cbranch_scc1 .Ltsk689_d2
	s_cmp_le_u32 s49, s39
	s_cbranch_scc1 .LBB0_696
	v_subrev_u32_e32 v32, 64, v156
	v_cmp_lt_i32_e64 s[4:5], -1, v32
	v_cmp_lt_i32_e64 s[6:7], 31, v32
	v_cmp_lt_i32_e32 vcc, 0, v32
	v_cndmask_b32_e64 v80, v249, v80, s[4:5]
	v_cmp_lt_i32_e64 s[4:5], 32, v32
	v_cndmask_b32_e64 v64, v249, v64, s[6:7]
	v_cmp_lt_i32_e64 s[6:7], 1, v32
	v_cndmask_b32_e32 v81, v249, v81, vcc
	v_cmp_lt_i32_e32 vcc, 33, v32
	v_cndmask_b32_e64 v65, v249, v65, s[4:5]
	v_cmp_lt_i32_e64 s[4:5], 2, v32
	v_cndmask_b32_e64 v82, v249, v82, s[6:7]
	v_cmp_lt_i32_e64 s[6:7], 34, v32
	v_cndmask_b32_e32 v66, v249, v66, vcc
	v_cmp_lt_i32_e32 vcc, 7, v32
	v_cndmask_b32_e64 v83, v249, v83, s[4:5]
	v_cmp_lt_i32_e64 s[4:5], 39, v32
	v_cndmask_b32_e64 v67, v249, v67, s[6:7]
	v_cmp_lt_i32_e64 s[6:7], 8, v32
	v_cndmask_b32_e32 v84, v249, v84, vcc
	v_cmp_lt_i32_e32 vcc, 40, v32
	v_cndmask_b32_e64 v68, v249, v68, s[4:5]
	v_cmp_lt_i32_e64 s[4:5], 9, v32
	v_cndmask_b32_e64 v85, v249, v85, s[6:7]
	v_cmp_lt_i32_e64 s[6:7], 41, v32
	v_cndmask_b32_e32 v69, v249, v69, vcc
	v_cmp_lt_i32_e32 vcc, 10, v32
	v_cndmask_b32_e64 v86, v249, v86, s[4:5]
	v_cmp_lt_i32_e64 s[4:5], 42, v32
	v_cndmask_b32_e64 v70, v249, v70, s[6:7]
	v_cmp_lt_i32_e64 s[6:7], 15, v32
	v_cndmask_b32_e32 v87, v249, v87, vcc
	v_cmp_lt_i32_e32 vcc, 47, v32
	v_cndmask_b32_e64 v71, v249, v71, s[4:5]
	v_cmp_lt_i32_e64 s[4:5], 16, v32
	v_cndmask_b32_e64 v88, v249, v88, s[6:7]
	v_cmp_lt_i32_e64 s[6:7], 48, v32
	v_cndmask_b32_e32 v72, v249, v72, vcc
	v_cmp_lt_i32_e32 vcc, 17, v32
	v_cndmask_b32_e64 v89, v249, v89, s[4:5]
	v_cmp_lt_i32_e64 s[4:5], 49, v32
	v_cndmask_b32_e64 v73, v249, v73, s[6:7]
	v_cmp_lt_i32_e64 s[6:7], 18, v32
	v_cndmask_b32_e32 v90, v249, v90, vcc
	v_cmp_lt_i32_e32 vcc, 50, v32
	v_cndmask_b32_e64 v74, v249, v74, s[4:5]
	v_cmp_lt_i32_e64 s[4:5], 23, v32
	v_cndmask_b32_e64 v91, v249, v91, s[6:7]
	v_cmp_lt_i32_e64 s[6:7], 55, v32
	v_cndmask_b32_e32 v75, v249, v75, vcc
	v_cmp_lt_i32_e32 vcc, 24, v32
	v_cndmask_b32_e64 v92, v249, v92, s[4:5]
	v_cmp_lt_i32_e64 s[4:5], 56, v32
	v_cndmask_b32_e64 v76, v249, v76, s[6:7]
	v_cmp_lt_i32_e64 s[6:7], 25, v32
	v_cndmask_b32_e32 v93, v249, v93, vcc
	v_cmp_lt_i32_e32 vcc, 57, v32
	v_cndmask_b32_e64 v77, v249, v77, s[4:5]
	v_cmp_lt_i32_e64 s[4:5], 26, v32
	v_cndmask_b32_e64 v94, v249, v94, s[6:7]
	v_cmp_lt_i32_e64 s[6:7], 58, v32
	v_cndmask_b32_e32 v78, v249, v78, vcc
	s_nop 0
	v_cndmask_b32_e64 v95, v249, v95, s[4:5]
	s_nop 0
	v_cndmask_b32_e64 v79, v249, v79, s[6:7]

; template <int DQK, int MODE> ...
;     ...
;     for (int kt = kt_lo; kt <= kt_hi; kt += 2) {
;         AT_STEPF(pa0, pa1, pb0, pb1, kt);
;         if (kt + 1 <= kt_hi) AT_STEPF(pb0, pb1, pa0, pa1, kt + 1);
;     }
.Ltsk689_d1:
	s_waitcnt vmcnt(2) lgkmcnt(0)
	s_barrier
	s_add_i32 s4, s21, -4
	s_cmp_ge_u32 s4, s43
	s_cbranch_scc1 .LBB0_688
	s_branch .Ltsk689_s2
.Ltsk689_d2:
	s_waitcnt vmcnt(2) lgkmcnt(0)
	s_barrier
	s_branch .LBB0_688

.LBB0_717:
	s_add_i32 s4, s19, -1
	s_min_u32 s44, s4, s22
	s_mul_hi_u32 s4, s44, 0x55555556
	s_mul_i32 s4, s4, 3
	s_sub_i32 s4, s44, s4
	s_mulk_i32 s4, 0x5000
	s_add_i32 s42, s19, -2
	s_add_i32 s45, s4, 0
	s_min_u32 s4, s42, s22
	s_mul_hi_u32 s5, s4, 0x55555556
	s_mul_i32 s5, s5, 3
	s_sub_i32 s5, s4, s5
	s_mul_i32 s80, s44, 0xc000
	s_mulk_i32 s5, 0x5000
	v_lshl_add_u64 v[80:81], v[184:185], 0, s[80:81]
	s_add_i32 m0, s45, s63
	s_add_i32 s43, s5, 0
	global_load_lds_dwordx4 v[80:81], off
	v_lshl_add_u64 v[80:81], v[186:187], 0, s[80:81]
	s_add_i32 m0, s45, s75
	s_lshl_b32 s80, s4, 15
	s_add_i32 s4, s43, s95
	global_load_lds_dwordx4 v[80:81], off
	v_lshl_add_u64 v[80:81], v[188:189], 0, s[80:81]
	s_add_i32 m0, s4, 0x3000
	s_sub_i32 s4, s23, 64
	global_load_lds_dwordx4 v[80:81], off
	s_cmp_le_u32 s4, s39
	s_sub_i32 s5, s4, 94
	s_cmp_gt_i32 s5, s39
	s_cbranch_scc1 .Ltsk717_d1
	s_cmp_le_u32 s4, s39
	s_cbranch_scc1 .LBB0_719
	v_cmp_lt_i32_e64 s[4:5], -1, v196
	v_cmp_lt_i32_e64 s[6:7], 31, v196
	v_cmp_lt_i32_e32 vcc, 0, v196
	v_cndmask_b32_e64 v48, v249, v48, s[4:5]
	v_cmp_lt_i32_e64 s[4:5], 32, v196
	v_cndmask_b32_e64 v64, v249, v64, s[6:7]
	v_cmp_lt_i32_e64 s[6:7], 1, v196
	v_cndmask_b32_e32 v49, v249, v49, vcc
	v_cmp_lt_i32_e32 vcc, 33, v196
	v_cndmask_b32_e64 v65, v249, v65, s[4:5]
	v_cmp_lt_i32_e64 s[4:5], 2, v196
	v_cndmask_b32_e64 v50, v249, v50, s[6:7]
	v_cmp_lt_i32_e64 s[6:7], 34, v196
	v_cndmask_b32_e32 v66, v249, v66, vcc
	v_cmp_lt_i32_e32 vcc, 7, v196
	v_cndmask_b32_e64 v51, v249, v51, s[4:5]
	v_cmp_lt_i32_e64 s[4:5], 39, v196
	v_cndmask_b32_e64 v67, v249, v67, s[6:7]
	v_cmp_lt_i32_e64 s[6:7], 8, v196
	v_cndmask_b32_e32 v52, v249, v52, vcc
	v_cmp_lt_i32_e32 vcc, 40, v196
	v_cndmask_b32_e64 v68, v249, v68, s[4:5]
	v_cmp_lt_i32_e64 s[4:5], 9, v196
	v_cndmask_b32_e64 v53, v249, v53, s[6:7]
	v_cmp_lt_i32_e64 s[6:7], 41, v196
	v_cndmask_b32_e32 v69, v249, v69, vcc
	v_cmp_lt_i32_e32 vcc, 10, v196
	v_cndmask_b32_e64 v54, v249, v54, s[4:5]
	v_cmp_lt_i32_e64 s[4:5], 42, v196
	v_cndmask_b32_e64 v70, v249, v70, s[6:7]
	v_cmp_lt_i32_e64 s[6:7], 15, v196
	v_cndmask_b32_e32 v55, v249, v55, vcc
	v_cmp_lt_i32_e32 vcc, 47, v196
	v_cndmask_b32_e64 v71, v249, v71, s[4:5]
	v_cmp_lt_i32_e64 s[4:5], 16, v196
	v_cndmask_b32_e64 v56, v249, v56, s[6:7]
	v_cmp_lt_i32_e64 s[6:7], 48, v196
	v_cndmask_b32_e32 v72, v249, v72, vcc
	v_cmp_lt_i32_e32 vcc, 17, v196
	v_cndmask_b32_e64 v57, v249, v57, s[4:5]
	v_cmp_lt_i32_e64 s[4:5], 49, v196
	v_cndmask_b32_e64 v73, v249, v73, s[6:7]
	v_cmp_lt_i32_e64 s[6:7], 18, v196
	v_cndmask_b32_e32 v58, v249, v58, vcc
	v_cmp_lt_i32_e32 vcc, 50, v196
	v_cndmask_b32_e64 v74, v249, v74, s[4:5]
	v_cmp_lt_i32_e64 s[4:5], 23, v196
	v_cndmask_b32_e64 v59, v249, v59, s[6:7]
	v_cmp_lt_i32_e64 s[6:7], 55, v196
	v_cndmask_b32_e32 v75, v249, v75, vcc
	v_cmp_lt_i32_e32 vcc, 24, v196
	v_cndmask_b32_e64 v60, v249, v60, s[4:5]
	v_cmp_lt_i32_e64 s[4:5], 56, v196
	v_cndmask_b32_e64 v76, v249, v76, s[6:7]
	v_cmp_lt_i32_e64 s[6:7], 25, v196
	v_cndmask_b32_e32 v61, v249, v61, vcc
	v_cmp_lt_i32_e32 vcc, 57, v196
	v_cndmask_b32_e64 v77, v249, v77, s[4:5]
	v_cmp_lt_i32_e64 s[4:5], 26, v196
	v_cndmask_b32_e64 v62, v249, v62, s[6:7]
	v_cmp_lt_i32_e64 s[6:7], 58, v196
	v_cndmask_b32_e32 v78, v249, v78, vcc
	s_nop 0
	v_cndmask_b32_e64 v63, v249, v63, s[4:5]
	s_nop 0
	v_cndmask_b32_e64 v79, v249, v79, s[6:7]

.Ltsk717_s2:
	s_min_u32 s4, s19, s22
	s_mul_hi_u32 s5, s4, 0x55555556
	s_mul_i32 s5, s5, 3
	s_sub_i32 s5, s4, s5
	s_mulk_i32 s5, 0x5000
	s_add_i32 s5, s5, 0
	s_mul_i32 s80, s4, 0xc000
	v_lshl_add_u64 v[48:49], v[184:185], 0, s[80:81]
	s_add_i32 m0, s5, s63
	s_add_i32 s4, s45, s95
	global_load_lds_dwordx4 v[48:49], off
	v_lshl_add_u64 v[48:49], v[186:187], 0, s[80:81]
	s_add_i32 m0, s5, s75
	s_lshl_b32 s80, s44, 15
	global_load_lds_dwordx4 v[48:49], off
	v_lshl_add_u64 v[48:49], v[188:189], 0, s[80:81]
	s_add_i32 m0, s4, 0x3000
	s_cmp_le_u32 s23, s39
	global_load_lds_dwordx4 v[48:49], off
	s_sub_i32 s5, s23, 94
	s_cmp_gt_i32 s5, s39
	s_cbranch_scc1 .Ltsk717_d2
	s_cmp_le_u32 s23, s39
	s_cbranch_scc1 .LBB0_724
	v_subrev_u32_e32 v48, 64, v196
	v_cmp_lt_i32_e64 s[4:5], -1, v48
	v_cmp_lt_i32_e64 s[6:7], 31, v48
	v_cmp_lt_i32_e32 vcc, 0, v48
	v_cndmask_b32_e64 v96, v249, v96, s[4:5]
	v_cmp_lt_i32_e64 s[4:5], 32, v48
	v_cndmask_b32_e64 v80, v249, v80, s[6:7]
	v_cmp_lt_i32_e64 s[6:7], 1, v48
	v_cndmask_b32_e32 v97, v249, v97, vcc
	v_cmp_lt_i32_e32 vcc, 33, v48
	v_cndmask_b32_e64 v81, v249, v81, s[4:5]
	v_cmp_lt_i32_e64 s[4:5], 2, v48
	v_cndmask_b32_e64 v98, v249, v98, s[6:7]
	v_cmp_lt_i32_e64 s[6:7], 34, v48
	v_cndmask_b32_e32 v82, v249, v82, vcc
	v_cmp_lt_i32_e32 vcc, 7, v48
	v_cndmask_b32_e64 v99, v249, v99, s[4:5]
	v_cmp_lt_i32_e64 s[4:5], 39, v48
	v_cndmask_b32_e64 v83, v249, v83, s[6:7]
	v_cmp_lt_i32_e64 s[6:7], 8, v48
	v_cndmask_b32_e32 v100, v249, v100, vcc
	v_cmp_lt_i32_e32 vcc, 40, v48
	v_cndmask_b32_e64 v84, v249, v84, s[4:5]
	v_cmp_lt_i32_e64 s[4:5], 9, v48
	v_cndmask_b32_e64 v101, v249, v101, s[6:7]
	v_cmp_lt_i32_e64 s[6:7], 41, v48
	v_cndmask_b32_e32 v85, v249, v85, vcc
	v_cmp_lt_i32_e32 vcc, 10, v48
	v_cndmask_b32_e64 v102, v249, v102, s[4:5]
	v_cmp_lt_i32_e64 s[4:5], 42, v48
	v_cndmask_b32_e64 v86, v249, v86, s[6:7]
	v_cmp_lt_i32_e64 s[6:7], 15, v48
	v_cndmask_b32_e32 v103, v249, v103, vcc
	v_cmp_lt_i32_e32 vcc, 47, v48
	v_cndmask_b32_e64 v87, v249, v87, s[4:5]
	v_cmp_lt_i32_e64 s[4:5], 16, v48
	v_cndmask_b32_e64 v104, v249, v104, s[6:7]
	v_cmp_lt_i32_e64 s[6:7], 48, v48
	v_cndmask_b32_e32 v88, v249, v88, vcc
	v_cmp_lt_i32_e32 vcc, 17, v48
	v_cndmask_b32_e64 v105, v249, v105, s[4:5]
	v_cmp_lt_i32_e64 s[4:5], 49, v48
	v_cndmask_b32_e64 v89, v249, v89, s[6:7]
	v_cmp_lt_i32_e64 s[6:7], 18, v48
	v_cndmask_b32_e32 v106, v249, v106, vcc
	v_cmp_lt_i32_e32 vcc, 50, v48
	v_cndmask_b32_e64 v90, v249, v90, s[4:5]
	v_cmp_lt_i32_e64 s[4:5], 23, v48
	v_cndmask_b32_e64 v107, v249, v107, s[6:7]
	v_cmp_lt_i32_e64 s[6:7], 55, v48
	v_cndmask_b32_e32 v91, v249, v91, vcc
	v_cmp_lt_i32_e32 vcc, 24, v48
	v_cndmask_b32_e64 v108, v249, v108, s[4:5]
	v_cmp_lt_i32_e64 s[4:5], 56, v48
	v_cndmask_b32_e64 v92, v249, v92, s[6:7]
	v_cmp_lt_i32_e64 s[6:7], 25, v48
	v_cndmask_b32_e32 v109, v249, v109, vcc
	v_cmp_lt_i32_e32 vcc, 57, v48
	v_cndmask_b32_e64 v93, v249, v93, s[4:5]
	v_cmp_lt_i32_e64 s[4:5], 26, v48
	v_cndmask_b32_e64 v110, v249, v110, s[6:7]
	v_cmp_lt_i32_e64 s[6:7], 58, v48
	v_cndmask_b32_e32 v94, v249, v94, vcc
	s_nop 0
	v_cndmask_b32_e64 v111, v249, v111, s[4:5]
	s_nop 0
	v_cndmask_b32_e64 v95, v249, v95, s[6:7]

; template <int DQK, int MODE> ...
;     ...
;     for (int kt = kt_lo; kt <= kt_hi; kt += 2) {
;         AT_STEPF(pa0, pa1, pb0, pb1, kt);
;         if (kt + 1 <= kt_hi) AT_STEPF(pb0, pb1, pa0, pa1, kt + 1);
;     }
.Ltsk717_d1:
	s_waitcnt vmcnt(3) lgkmcnt(0)
	s_barrier
	s_add_i32 s4, s19, -4
	s_cmp_ge_u32 s4, s22
	s_cbranch_scc1 .LBB0_716
	s_branch .Ltsk717_s2
.Ltsk717_d2:
	s_waitcnt vmcnt(3) lgkmcnt(0)
	s_barrier
	s_branch .LBB0_716

.LBB0_732:
	s_add_i32 s4, s21, -1
	s_min_u32 s4, s4, s40
	s_mul_hi_u32 s5, s4, 0x55555556
	s_mul_i32 s5, s5, 3
	s_sub_i32 s5, s4, s5
	s_mul_i32 s4, s4, 0x28000
	s_add_i32 s46, s21, -2
	s_mulk_i32 s5, 0x3000
	s_lshl_b32 s80, s4, 1
	s_min_u32 s4, s46, s40
	s_add_i32 s48, s5, 0
	s_mul_hi_u32 s5, s4, 0x55555556
	s_mul_i32 s5, s5, 3
	s_sub_i32 s5, s4, s5
	v_lshl_add_u64 v[80:81], v[128:129], 0, s[80:81]
	s_mulk_i32 s5, 0x3000
	v_lshl_add_u64 v[80:81], v[80:81], 0, s[76:77]
	s_add_i32 m0, s48, s92
	s_add_i32 s47, s5, 0
	s_mul_i32 s4, s4, 0x50000
	s_mov_b32 s5, s81
	global_load_lds_dwordx4 v[80:81], off
	v_lshl_add_u64 v[80:81], v[130:131], 0, s[4:5]
	s_add_i32 s4, s47, s95
	v_lshl_add_u64 v[80:81], v[80:81], 0, s[0:1]
	s_add_i32 m0, s4, 0x1000
	s_sub_i32 s4, s45, 64
	global_load_lds_dwordx4 v[80:81], off
	s_cmp_le_u32 s4, s39
	s_sub_i32 s5, s4, 94
	s_cmp_gt_i32 s5, s39
	s_cbranch_scc1 .Ltsk732_d1
	s_cmp_le_u32 s4, s39
	s_cbranch_scc1 .LBB0_734
	v_cmp_lt_i32_e64 s[4:5], -1, v136
	v_cmp_lt_i32_e64 s[6:7], 31, v136
	v_cmp_lt_i32_e32 vcc, 0, v136
	v_cndmask_b32_e64 v48, v249, v48, s[4:5]
	v_cmp_lt_i32_e64 s[4:5], 32, v136
	v_cndmask_b32_e64 v64, v249, v64, s[6:7]
	v_cmp_lt_i32_e64 s[6:7], 1, v136
	v_cndmask_b32_e32 v49, v249, v49, vcc
	v_cmp_lt_i32_e32 vcc, 33, v136
	v_cndmask_b32_e64 v65, v249, v65, s[4:5]
	v_cmp_lt_i32_e64 s[4:5], 2, v136
	v_cndmask_b32_e64 v50, v249, v50, s[6:7]
	v_cmp_lt_i32_e64 s[6:7], 34, v136
	v_cndmask_b32_e32 v66, v249, v66, vcc
	v_cmp_lt_i32_e32 vcc, 7, v136
	v_cndmask_b32_e64 v51, v249, v51, s[4:5]
	v_cmp_lt_i32_e64 s[4:5], 39, v136
	v_cndmask_b32_e64 v67, v249, v67, s[6:7]
	v_cmp_lt_i32_e64 s[6:7], 8, v136
	v_cndmask_b32_e32 v52, v249, v52, vcc
	v_cmp_lt_i32_e32 vcc, 40, v136
	v_cndmask_b32_e64 v68, v249, v68, s[4:5]
	v_cmp_lt_i32_e64 s[4:5], 9, v136
	v_cndmask_b32_e64 v53, v249, v53, s[6:7]
	v_cmp_lt_i32_e64 s[6:7], 41, v136
	v_cndmask_b32_e32 v69, v249, v69, vcc
	v_cmp_lt_i32_e32 vcc, 10, v136
	v_cndmask_b32_e64 v54, v249, v54, s[4:5]
	v_cmp_lt_i32_e64 s[4:5], 42, v136
	v_cndmask_b32_e64 v70, v249, v70, s[6:7]
	v_cmp_lt_i32_e64 s[6:7], 15, v136
	v_cndmask_b32_e32 v55, v249, v55, vcc
	v_cmp_lt_i32_e32 vcc, 47, v136
	v_cndmask_b32_e64 v71, v249, v71, s[4:5]
	v_cmp_lt_i32_e64 s[4:5], 16, v136
	v_cndmask_b32_e64 v56, v249, v56, s[6:7]
	v_cmp_lt_i32_e64 s[6:7], 48, v136
	v_cndmask_b32_e32 v72, v249, v72, vcc
	v_cmp_lt_i32_e32 vcc, 17, v136
	v_cndmask_b32_e64 v57, v249, v57, s[4:5]
	v_cmp_lt_i32_e64 s[4:5], 49, v136
	v_cndmask_b32_e64 v73, v249, v73, s[6:7]
	v_cmp_lt_i32_e64 s[6:7], 18, v136
	v_cndmask_b32_e32 v58, v249, v58, vcc
	v_cmp_lt_i32_e32 vcc, 50, v136
	v_cndmask_b32_e64 v74, v249, v74, s[4:5]
	v_cmp_lt_i32_e64 s[4:5], 23, v136
	v_cndmask_b32_e64 v59, v249, v59, s[6:7]
	v_cmp_lt_i32_e64 s[6:7], 55, v136
	v_cndmask_b32_e32 v75, v249, v75, vcc
	v_cmp_lt_i32_e32 vcc, 24, v136
	v_cndmask_b32_e64 v60, v249, v60, s[4:5]
	v_cmp_lt_i32_e64 s[4:5], 56, v136
	v_cndmask_b32_e64 v76, v249, v76, s[6:7]
	v_cmp_lt_i32_e64 s[6:7], 25, v136
	v_cndmask_b32_e32 v61, v249, v61, vcc
	v_cmp_lt_i32_e32 vcc, 57, v136
	v_cndmask_b32_e64 v77, v249, v77, s[4:5]
	v_cmp_lt_i32_e64 s[4:5], 26, v136
	v_cndmask_b32_e64 v62, v249, v62, s[6:7]
	v_cmp_lt_i32_e64 s[6:7], 58, v136
	v_cndmask_b32_e32 v78, v249, v78, vcc
	s_nop 0
	v_cndmask_b32_e64 v63, v249, v63, s[4:5]
	s_nop 0
	v_cndmask_b32_e64 v79, v249, v79, s[6:7]

.Ltsk732_s2:
	s_min_u32 s4, s21, s40
	s_mul_hi_u32 s5, s4, 0x55555556
	s_mul_i32 s5, s5, 3
	s_sub_i32 s5, s4, s5
	s_mul_i32 s6, s5, 0x3000
	s_mul_i32 s4, s4, 0x50000
	s_mov_b32 s5, s81
	v_lshl_add_u64 v[48:49], v[128:129], 0, s[4:5]
	v_lshl_add_u64 v[48:49], v[48:49], 0, s[76:77]
	s_add_i32 m0, s93, s6
	s_add_i32 s4, s48, s95
	global_load_lds_dwordx4 v[48:49], off
	v_lshl_add_u64 v[48:49], v[130:131], 0, s[80:81]
	v_lshl_add_u64 v[48:49], v[48:49], 0, s[0:1]
	s_add_i32 m0, s4, 0x1000
	s_cmp_le_u32 s45, s39
	global_load_lds_dwordx4 v[48:49], off
	s_sub_i32 s5, s45, 94
	s_cmp_gt_i32 s5, s39
	s_cbranch_scc1 .Ltsk732_d2
	s_cmp_le_u32 s45, s39
	s_cbranch_scc1 .LBB0_739
	v_subrev_u32_e32 v48, 64, v136
	v_cmp_lt_i32_e64 s[4:5], -1, v48
	v_cmp_lt_i32_e64 s[6:7], 31, v48
	v_cmp_lt_i32_e32 vcc, 0, v48
	v_cndmask_b32_e64 v96, v249, v96, s[4:5]
	v_cmp_lt_i32_e64 s[4:5], 32, v48
	v_cndmask_b32_e64 v80, v249, v80, s[6:7]
	v_cmp_lt_i32_e64 s[6:7], 1, v48
	v_cndmask_b32_e32 v97, v249, v97, vcc
	v_cmp_lt_i32_e32 vcc, 33, v48
	v_cndmask_b32_e64 v81, v249, v81, s[4:5]
	v_cmp_lt_i32_e64 s[4:5], 2, v48
	v_cndmask_b32_e64 v98, v249, v98, s[6:7]
	v_cmp_lt_i32_e64 s[6:7], 34, v48
	v_cndmask_b32_e32 v82, v249, v82, vcc
	v_cmp_lt_i32_e32 vcc, 7, v48
	v_cndmask_b32_e64 v99, v249, v99, s[4:5]
	v_cmp_lt_i32_e64 s[4:5], 39, v48
	v_cndmask_b32_e64 v83, v249, v83, s[6:7]
	v_cmp_lt_i32_e64 s[6:7], 8, v48
	v_cndmask_b32_e32 v100, v249, v100, vcc
	v_cmp_lt_i32_e32 vcc, 40, v48
	v_cndmask_b32_e64 v84, v249, v84, s[4:5]
	v_cmp_lt_i32_e64 s[4:5], 9, v48
	v_cndmask_b32_e64 v101, v249, v101, s[6:7]
	v_cmp_lt_i32_e64 s[6:7], 41, v48
	v_cndmask_b32_e32 v85, v249, v85, vcc
	v_cmp_lt_i32_e32 vcc, 10, v48
	v_cndmask_b32_e64 v102, v249, v102, s[4:5]
	v_cmp_lt_i32_e64 s[4:5], 42, v48
	v_cndmask_b32_e64 v86, v249, v86, s[6:7]
	v_cmp_lt_i32_e64 s[6:7], 15, v48
	v_cndmask_b32_e32 v103, v249, v103, vcc
	v_cmp_lt_i32_e32 vcc, 47, v48
	v_cndmask_b32_e64 v87, v249, v87, s[4:5]
	v_cmp_lt_i32_e64 s[4:5], 16, v48
	v_cndmask_b32_e64 v104, v249, v104, s[6:7]
	v_cmp_lt_i32_e64 s[6:7], 48, v48
	v_cndmask_b32_e32 v88, v249, v88, vcc
	v_cmp_lt_i32_e32 vcc, 17, v48
	v_cndmask_b32_e64 v105, v249, v105, s[4:5]
	v_cmp_lt_i32_e64 s[4:5], 49, v48
	v_cndmask_b32_e64 v89, v249, v89, s[6:7]
	v_cmp_lt_i32_e64 s[6:7], 18, v48
	v_cndmask_b32_e32 v106, v249, v106, vcc
	v_cmp_lt_i32_e32 vcc, 50, v48
	v_cndmask_b32_e64 v90, v249, v90, s[4:5]
	v_cmp_lt_i32_e64 s[4:5], 23, v48
	v_cndmask_b32_e64 v107, v249, v107, s[6:7]
	v_cmp_lt_i32_e64 s[6:7], 55, v48
	v_cndmask_b32_e32 v91, v249, v91, vcc
	v_cmp_lt_i32_e32 vcc, 24, v48
	v_cndmask_b32_e64 v108, v249, v108, s[4:5]
	v_cmp_lt_i32_e64 s[4:5], 56, v48
	v_cndmask_b32_e64 v92, v249, v92, s[6:7]
	v_cmp_lt_i32_e64 s[6:7], 25, v48
	v_cndmask_b32_e32 v109, v249, v109, vcc
	v_cmp_lt_i32_e32 vcc, 57, v48
	v_cndmask_b32_e64 v93, v249, v93, s[4:5]
	v_cmp_lt_i32_e64 s[4:5], 26, v48
	v_cndmask_b32_e64 v110, v249, v110, s[6:7]
	v_cmp_lt_i32_e64 s[6:7], 58, v48
	v_cndmask_b32_e32 v94, v249, v94, vcc
	s_nop 0
	v_cndmask_b32_e64 v111, v249, v111, s[4:5]
	s_nop 0
	v_cndmask_b32_e64 v95, v249, v95, s[6:7]

; template <int DQK, int MODE> ...
;     ...
;     for (int kt = kt_lo; kt <= kt_hi; kt += 2) {
;         AT_STEPF(pa0, pa1, pb0, pb1, kt);
;         if (kt + 1 <= kt_hi) AT_STEPF(pb0, pb1, pa0, pa1, kt + 1);
;     }
.Ltsk732_d1:
	s_waitcnt vmcnt(2) lgkmcnt(0)
	s_barrier
	s_add_i32 s4, s21, -4
	s_cmp_ge_u32 s4, s40
	s_cbranch_scc1 .LBB0_731
	s_branch .Ltsk732_s2

.LBB0_744:
	s_add_i32 s4, s17, -1
	s_min_u32 s4, s4, s40
	s_mul_hi_u32 s5, s4, 0x55555556
	s_mul_i32 s5, s5, 3
	s_sub_i32 s5, s4, s5
	s_mul_i32 s4, s4, 0x28000
	s_add_i32 s20, s17, -2
	s_mulk_i32 s5, 0x3000
	s_lshl_b32 s80, s4, 1
	s_min_u32 s4, s20, s40
	s_add_i32 s41, s5, 0
	s_mul_hi_u32 s5, s4, 0x55555556
	s_mul_i32 s5, s5, 3
	s_sub_i32 s5, s4, s5
	v_lshl_add_u64 v[80:81], v[128:129], 0, s[80:81]
	s_mulk_i32 s5, 0x3000
	v_lshl_add_u64 v[80:81], v[80:81], 0, s[90:91]
	s_add_i32 m0, s41, s92
	s_add_i32 s21, s5, 0
	s_mul_i32 s4, s4, 0x50000
	s_mov_b32 s5, s81
	global_load_lds_dwordx4 v[80:81], off
	v_lshl_add_u64 v[80:81], v[130:131], 0, s[4:5]
	s_add_i32 s4, s21, s95
	v_lshl_add_u64 v[80:81], v[80:81], 0, s[0:1]
	s_add_i32 m0, s4, 0x1000
	s_sub_i32 s4, s19, 64
	global_load_lds_dwordx4 v[80:81], off
	s_cmp_le_u32 s4, s39
	s_sub_i32 s5, s4, 94
	s_cmp_gt_i32 s5, s39
	s_cbranch_scc1 .Ltsk744_d1
	s_cmp_le_u32 s4, s39
	s_cbranch_scc1 .LBB0_746
	v_cmp_lt_i32_e64 s[4:5], -1, v137
	v_cmp_lt_i32_e64 s[6:7], 31, v137
	v_cmp_lt_i32_e32 vcc, 0, v137
	v_cndmask_b32_e64 v48, v249, v48, s[4:5]
	v_cmp_lt_i32_e64 s[4:5], 32, v137
	v_cndmask_b32_e64 v64, v249, v64, s[6:7]
	v_cmp_lt_i32_e64 s[6:7], 1, v137
	v_cndmask_b32_e32 v49, v249, v49, vcc
	v_cmp_lt_i32_e32 vcc, 33, v137
	v_cndmask_b32_e64 v65, v249, v65, s[4:5]
	v_cmp_lt_i32_e64 s[4:5], 2, v137
	v_cndmask_b32_e64 v50, v249, v50, s[6:7]
	v_cmp_lt_i32_e64 s[6:7], 34, v137
	v_cndmask_b32_e32 v66, v249, v66, vcc
	v_cmp_lt_i32_e32 vcc, 7, v137
	v_cndmask_b32_e64 v51, v249, v51, s[4:5]
	v_cmp_lt_i32_e64 s[4:5], 39, v137
	v_cndmask_b32_e64 v67, v249, v67, s[6:7]
	v_cmp_lt_i32_e64 s[6:7], 8, v137
	v_cndmask_b32_e32 v52, v249, v52, vcc
	v_cmp_lt_i32_e32 vcc, 40, v137
	v_cndmask_b32_e64 v68, v249, v68, s[4:5]
	v_cmp_lt_i32_e64 s[4:5], 9, v137
	v_cndmask_b32_e64 v53, v249, v53, s[6:7]
	v_cmp_lt_i32_e64 s[6:7], 41, v137
	v_cndmask_b32_e32 v69, v249, v69, vcc
	v_cmp_lt_i32_e32 vcc, 10, v137
	v_cndmask_b32_e64 v54, v249, v54, s[4:5]
	v_cmp_lt_i32_e64 s[4:5], 42, v137
	v_cndmask_b32_e64 v70, v249, v70, s[6:7]
	v_cmp_lt_i32_e64 s[6:7], 15, v137
	v_cndmask_b32_e32 v55, v249, v55, vcc
	v_cmp_lt_i32_e32 vcc, 47, v137
	v_cndmask_b32_e64 v71, v249, v71, s[4:5]
	v_cmp_lt_i32_e64 s[4:5], 16, v137
	v_cndmask_b32_e64 v56, v249, v56, s[6:7]
	v_cmp_lt_i32_e64 s[6:7], 48, v137
	v_cndmask_b32_e32 v72, v249, v72, vcc
	v_cmp_lt_i32_e32 vcc, 17, v137
	v_cndmask_b32_e64 v57, v249, v57, s[4:5]
	v_cmp_lt_i32_e64 s[4:5], 49, v137
	v_cndmask_b32_e64 v73, v249, v73, s[6:7]
	v_cmp_lt_i32_e64 s[6:7], 18, v137
	v_cndmask_b32_e32 v58, v249, v58, vcc
	v_cmp_lt_i32_e32 vcc, 50, v137
	v_cndmask_b32_e64 v74, v249, v74, s[4:5]
	v_cmp_lt_i32_e64 s[4:5], 23, v137
	v_cndmask_b32_e64 v59, v249, v59, s[6:7]
	v_cmp_lt_i32_e64 s[6:7], 55, v137
	v_cndmask_b32_e32 v75, v249, v75, vcc
	v_cmp_lt_i32_e32 vcc, 24, v137
	v_cndmask_b32_e64 v60, v249, v60, s[4:5]
	v_cmp_lt_i32_e64 s[4:5], 56, v137
	v_cndmask_b32_e64 v76, v249, v76, s[6:7]
	v_cmp_lt_i32_e64 s[6:7], 25, v137
	v_cndmask_b32_e32 v61, v249, v61, vcc
	v_cmp_lt_i32_e32 vcc, 57, v137
	v_cndmask_b32_e64 v77, v249, v77, s[4:5]
	v_cmp_lt_i32_e64 s[4:5], 26, v137
	v_cndmask_b32_e64 v62, v249, v62, s[6:7]
	v_cmp_lt_i32_e64 s[6:7], 58, v137
	v_cndmask_b32_e32 v78, v249, v78, vcc
	s_nop 0
	v_cndmask_b32_e64 v63, v249, v63, s[4:5]
	s_nop 0
	v_cndmask_b32_e64 v79, v249, v79, s[6:7]

.Ltsk744_s2:
	s_min_u32 s4, s17, s40
	s_mul_hi_u32 s5, s4, 0x55555556
	s_mul_i32 s5, s5, 3
	s_sub_i32 s5, s4, s5
	s_mul_i32 s6, s5, 0x3000
	s_mul_i32 s4, s4, 0x50000
	s_mov_b32 s5, s81
	v_lshl_add_u64 v[48:49], v[128:129], 0, s[4:5]
	v_lshl_add_u64 v[48:49], v[48:49], 0, s[90:91]
	s_add_i32 m0, s93, s6
	s_add_i32 s4, s41, s95
	global_load_lds_dwordx4 v[48:49], off
	v_lshl_add_u64 v[48:49], v[130:131], 0, s[80:81]
	v_lshl_add_u64 v[48:49], v[48:49], 0, s[0:1]
	s_add_i32 m0, s4, 0x1000
	s_cmp_le_u32 s19, s39
	global_load_lds_dwordx4 v[48:49], off
	s_sub_i32 s5, s19, 94
	s_cmp_gt_i32 s5, s39
	s_cbranch_scc1 .Ltsk744_d2
	s_cmp_le_u32 s19, s39
	s_cbranch_scc1 .LBB0_751
	v_subrev_u32_e32 v48, 64, v137
	v_cmp_lt_i32_e64 s[4:5], -1, v48
	v_cmp_lt_i32_e64 s[6:7], 31, v48
	v_cmp_lt_i32_e32 vcc, 0, v48
	v_cndmask_b32_e64 v96, v249, v96, s[4:5]
	v_cmp_lt_i32_e64 s[4:5], 32, v48
	v_cndmask_b32_e64 v80, v249, v80, s[6:7]
	v_cmp_lt_i32_e64 s[6:7], 1, v48
	v_cndmask_b32_e32 v97, v249, v97, vcc
	v_cmp_lt_i32_e32 vcc, 33, v48
	v_cndmask_b32_e64 v81, v249, v81, s[4:5]
	v_cmp_lt_i32_e64 s[4:5], 2, v48
	v_cndmask_b32_e64 v98, v249, v98, s[6:7]
	v_cmp_lt_i32_e64 s[6:7], 34, v48
	v_cndmask_b32_e32 v82, v249, v82, vcc
	v_cmp_lt_i32_e32 vcc, 7, v48
	v_cndmask_b32_e64 v99, v249, v99, s[4:5]
	v_cmp_lt_i32_e64 s[4:5], 39, v48
	v_cndmask_b32_e64 v83, v249, v83, s[6:7]
	v_cmp_lt_i32_e64 s[6:7], 8, v48
	v_cndmask_b32_e32 v100, v249, v100, vcc
	v_cmp_lt_i32_e32 vcc, 40, v48
	v_cndmask_b32_e64 v84, v249, v84, s[4:5]
	v_cmp_lt_i32_e64 s[4:5], 9, v48
	v_cndmask_b32_e64 v101, v249, v101, s[6:7]
	v_cmp_lt_i32_e64 s[6:7], 41, v48
	v_cndmask_b32_e32 v85, v249, v85, vcc
	v_cmp_lt_i32_e32 vcc, 10, v48
	v_cndmask_b32_e64 v102, v249, v102, s[4:5]
	v_cmp_lt_i32_e64 s[4:5], 42, v48
	v_cndmask_b32_e64 v86, v249, v86, s[6:7]
	v_cmp_lt_i32_e64 s[6:7], 15, v48
	v_cndmask_b32_e32 v103, v249, v103, vcc
	v_cmp_lt_i32_e32 vcc, 47, v48
	v_cndmask_b32_e64 v87, v249, v87, s[4:5]
	v_cmp_lt_i32_e64 s[4:5], 16, v48
	v_cndmask_b32_e64 v104, v249, v104, s[6:7]
	v_cmp_lt_i32_e64 s[6:7], 48, v48
	v_cndmask_b32_e32 v88, v249, v88, vcc
	v_cmp_lt_i32_e32 vcc, 17, v48
	v_cndmask_b32_e64 v105, v249, v105, s[4:5]
	v_cmp_lt_i32_e64 s[4:5], 49, v48
	v_cndmask_b32_e64 v89, v249, v89, s[6:7]
	v_cmp_lt_i32_e64 s[6:7], 18, v48
	v_cndmask_b32_e32 v106, v249, v106, vcc
	v_cmp_lt_i32_e32 vcc, 50, v48
	v_cndmask_b32_e64 v90, v249, v90, s[4:5]
	v_cmp_lt_i32_e64 s[4:5], 23, v48
	v_cndmask_b32_e64 v107, v249, v107, s[6:7]
	v_cmp_lt_i32_e64 s[6:7], 55, v48
	v_cndmask_b32_e32 v91, v249, v91, vcc
	v_cmp_lt_i32_e32 vcc, 24, v48
	v_cndmask_b32_e64 v108, v249, v108, s[4:5]
	v_cmp_lt_i32_e64 s[4:5], 56, v48
	v_cndmask_b32_e64 v92, v249, v92, s[6:7]
	v_cmp_lt_i32_e64 s[6:7], 25, v48
	v_cndmask_b32_e32 v109, v249, v109, vcc
	v_cmp_lt_i32_e32 vcc, 57, v48
	v_cndmask_b32_e64 v93, v249, v93, s[4:5]
	v_cmp_lt_i32_e64 s[4:5], 26, v48
	v_cndmask_b32_e64 v110, v249, v110, s[6:7]
	v_cmp_lt_i32_e64 s[6:7], 58, v48
	v_cndmask_b32_e32 v94, v249, v94, vcc
	s_nop 0
	v_cndmask_b32_e64 v111, v249, v111, s[4:5]
	s_nop 0
	v_cndmask_b32_e64 v95, v249, v95, s[6:7]

; template <int DQK, int MODE> ...
;     ...
;     for (int kt = kt_lo; kt <= kt_hi; kt += 2) {
;         AT_STEPF(pa0, pa1, pb0, pb1, kt);
;         if (kt + 1 <= kt_hi) AT_STEPF(pb0, pb1, pa0, pa1, kt + 1);
;     }
.Ltsk744_d1:
	s_waitcnt vmcnt(2) lgkmcnt(0)
	s_barrier
	s_add_i32 s4, s17, -4
	s_cmp_ge_u32 s4, s40
	s_cbranch_scc1 .LBB0_743
	s_branch .Ltsk744_s2
